# 32x32x16 attention loop: cost-weighted VALU spacing between MFMAs (exp counted double)
# speedup vs baseline: 1.0150x; 1.0150x over previous
.Lattn_nf_loop:
	s_and_b32 s10, s15, 1
	s_mul_i32 s6, s10, 0x8800
	v_add_u32_e32 v136, s6, v137
	v_add_u32_e32 v170, s6, v183
	s_sub_u32 s10, 0x8800, s6
	ds_read_b128 v[98:101], v136 offset:0
	ds_read_b128 v[102:105], v136 offset:32
	ds_read_b128 v[106:109], v136 offset:64
	ds_read_b128 v[110:113], v136 offset:96
	v_add_u32_e32 v171, s10, v126
	v_add_u32_e32 v173, s10, v127
	global_load_dwordx4 v[82:85], v124, s[64:65]
	global_load_dwordx4 v[86:89], v124, s[66:67]
	global_load_dwordx4 v[90:93], v124, s[68:69]
	global_load_dwordx4 v[94:97], v124, s[70:71]
	v_add_u32_e32 v124, s36, v124
	s_waitcnt lgkmcnt(3)
	v_mfma_f32_32x32x16_bf16 v[138:153], v[98:101], v[10:13], 0
	ds_read_b128 v[98:101], v136 offset:8704
	s_waitcnt lgkmcnt(3)
	v_mfma_f32_32x32x16_bf16 v[138:153], v[102:105], v[14:17], v[138:153]
	ds_read_b128 v[102:105], v136 offset:8736
	s_waitcnt lgkmcnt(3)
	v_mfma_f32_32x32x16_bf16 v[138:153], v[106:109], v[2:5], v[138:153]
	ds_read_b128 v[106:109], v136 offset:8768
	s_waitcnt lgkmcnt(3)
	v_mfma_f32_32x32x16_bf16 v[138:153], v[110:113], v[6:9], v[138:153]
	ds_read_b128 v[110:113], v136 offset:8800
	ds_read_b128 v[128:131], v170 offset:0
	ds_read_b128 v[184:187], v170 offset:8704
	ds_read_b128 v[188:191], v170 offset:17408
	ds_read_b128 v[192:195], v170 offset:26112
	s_waitcnt lgkmcnt(7)
	v_mfma_f32_32x32x16_bf16 v[154:169], v[98:101], v[10:13], 0
	ds_read_b128 v[98:101], v136 offset:17408
	s_nop 3
	v_exp_f32_e32 v138, v138
	v_exp_f32_e32 v139, v139
	v_exp_f32_e32 v140, v140
	v_exp_f32_e32 v141, v141
	v_exp_f32_e32 v142, v142
	v_exp_f32_e32 v143, v143
	s_waitcnt lgkmcnt(7)
	v_mfma_f32_32x32x16_bf16 v[154:169], v[102:105], v[14:17], v[154:169]
	ds_read_b128 v[102:105], v136 offset:17440
	v_exp_f32_e32 v144, v144
	v_exp_f32_e32 v145, v145
	v_add_f32_e32 v122, v138, v122
	v_add_f32_e32 v122, v139, v122
	v_add_f32_e32 v122, v140, v122
	v_add_f32_e32 v122, v141, v122
	v_add_f32_e32 v122, v142, v122
	v_add_f32_e32 v122, v143, v122
	v_add_f32_e32 v122, v144, v122
	v_add_f32_e32 v122, v145, v122
	v_cvt_pk_bf16_f32 v114, v138, v139
	v_cvt_pk_bf16_f32 v115, v140, v141
	v_cvt_pk_bf16_f32 v116, v142, v143
	v_cvt_pk_bf16_f32 v117, v144, v145
	ds_read_b128 v[196:199], v170 offset:32
	ds_read_b128 v[216:219], v170 offset:8736
	ds_read_b128 v[200:203], v170 offset:17440
	ds_read_b128 v[204:207], v170 offset:26144
	s_waitcnt lgkmcnt(11)
	v_mfma_f32_32x32x16_bf16 v[154:169], v[106:109], v[2:5], v[154:169]
	ds_read_b128 v[106:109], v136 offset:17472
	v_exp_f32_e32 v146, v146
	v_exp_f32_e32 v147, v147
	s_waitcnt lgkmcnt(11)
	v_mfma_f32_32x32x16_bf16 v[154:169], v[110:113], v[6:9], v[154:169]
	ds_read_b128 v[110:113], v136 offset:17504
	v_exp_f32_e32 v148, v148
	v_exp_f32_e32 v149, v149
	s_waitcnt lgkmcnt(11)
	v_mfma_f32_32x32x16_bf16 v[18:33], v[128:131], v[114:117], v[18:33]
	v_exp_f32_e32 v150, v150
	v_exp_f32_e32 v151, v151
	s_waitcnt lgkmcnt(10)
	v_mfma_f32_32x32x16_bf16 v[34:49], v[184:187], v[114:117], v[34:49]
	v_exp_f32_e32 v152, v152
	v_exp_f32_e32 v153, v153
	s_waitcnt lgkmcnt(9)
	v_mfma_f32_32x32x16_bf16 v[50:65], v[188:191], v[114:117], v[50:65]
	v_add_f32_e32 v122, v146, v122
	v_add_f32_e32 v122, v147, v122
	v_add_f32_e32 v122, v148, v122
	v_add_f32_e32 v122, v149, v122
	s_waitcnt lgkmcnt(8)
	v_mfma_f32_32x32x16_bf16 v[66:81], v[192:195], v[114:117], v[66:81]
	v_add_f32_e32 v122, v150, v122
	v_add_f32_e32 v122, v151, v122
	v_add_f32_e32 v122, v152, v122
	v_add_f32_e32 v122, v153, v122
	v_cvt_pk_bf16_f32 v118, v146, v147
	v_cvt_pk_bf16_f32 v119, v148, v149
	v_cvt_pk_bf16_f32 v120, v150, v151
	v_cvt_pk_bf16_f32 v121, v152, v153
	ds_read_b128 v[128:131], v170 offset:64
	ds_read_b128 v[184:187], v170 offset:8768
	ds_read_b128 v[188:191], v170 offset:17472
	ds_read_b128 v[192:195], v170 offset:26176
	s_waitcnt lgkmcnt(11)
	v_mfma_f32_32x32x16_bf16 v[138:153], v[98:101], v[10:13], 0
	ds_read_b128 v[98:101], v136 offset:26112
	v_exp_f32_e32 v154, v154
	v_exp_f32_e32 v155, v155
	s_waitcnt lgkmcnt(11)
	v_mfma_f32_32x32x16_bf16 v[138:153], v[102:105], v[14:17], v[138:153]
	ds_read_b128 v[102:105], v136 offset:26144
	v_exp_f32_e32 v156, v156
	v_exp_f32_e32 v157, v157
	s_waitcnt lgkmcnt(11)
	v_mfma_f32_32x32x16_bf16 v[18:33], v[196:199], v[118:121], v[18:33]
	v_exp_f32_e32 v158, v158
	v_exp_f32_e32 v159, v159
	s_waitcnt lgkmcnt(10)
	v_mfma_f32_32x32x16_bf16 v[34:49], v[216:219], v[118:121], v[34:49]
	v_exp_f32_e32 v160, v160
	v_exp_f32_e32 v161, v161
	s_waitcnt lgkmcnt(9)
	v_mfma_f32_32x32x16_bf16 v[50:65], v[200:203], v[118:121], v[50:65]
	v_add_f32_e32 v122, v154, v122
	v_add_f32_e32 v122, v155, v122
	v_add_f32_e32 v122, v156, v122
	v_add_f32_e32 v122, v157, v122
	s_waitcnt lgkmcnt(8)
	v_mfma_f32_32x32x16_bf16 v[66:81], v[204:207], v[118:121], v[66:81]
	v_add_f32_e32 v122, v158, v122
	v_add_f32_e32 v122, v159, v122
	v_add_f32_e32 v122, v160, v122
	v_add_f32_e32 v122, v161, v122
	v_cvt_pk_bf16_f32 v114, v154, v155
	v_cvt_pk_bf16_f32 v115, v156, v157
	v_cvt_pk_bf16_f32 v116, v158, v159
	v_cvt_pk_bf16_f32 v117, v160, v161
	ds_read_b128 v[196:199], v170 offset:96
	ds_read_b128 v[216:219], v170 offset:8800
	ds_read_b128 v[200:203], v170 offset:17504
	ds_read_b128 v[204:207], v170 offset:26208
	s_waitcnt lgkmcnt(11)
	v_mfma_f32_32x32x16_bf16 v[138:153], v[106:109], v[2:5], v[138:153]
	ds_read_b128 v[106:109], v136 offset:26176
	v_exp_f32_e32 v162, v162
	v_exp_f32_e32 v163, v163
	s_waitcnt lgkmcnt(11)
	v_mfma_f32_32x32x16_bf16 v[138:153], v[110:113], v[6:9], v[138:153]
	ds_read_b128 v[110:113], v136 offset:26208
	v_exp_f32_e32 v164, v164
	v_exp_f32_e32 v165, v165
	s_waitcnt lgkmcnt(11)
	v_mfma_f32_32x32x16_bf16 v[18:33], v[128:131], v[114:117], v[18:33]
	v_exp_f32_e32 v166, v166
	v_exp_f32_e32 v167, v167
	s_waitcnt lgkmcnt(10)
	v_mfma_f32_32x32x16_bf16 v[34:49], v[184:187], v[114:117], v[34:49]
	v_exp_f32_e32 v168, v168
	v_exp_f32_e32 v169, v169
	s_waitcnt lgkmcnt(9)
	v_mfma_f32_32x32x16_bf16 v[50:65], v[188:191], v[114:117], v[50:65]
	v_add_f32_e32 v122, v162, v122
	v_add_f32_e32 v122, v163, v122
	v_add_f32_e32 v122, v164, v122
	v_add_f32_e32 v122, v165, v122
	s_waitcnt lgkmcnt(8)
	v_mfma_f32_32x32x16_bf16 v[66:81], v[192:195], v[114:117], v[66:81]
	v_add_f32_e32 v122, v166, v122
	v_add_f32_e32 v122, v167, v122
	v_add_f32_e32 v122, v168, v122
	v_add_f32_e32 v122, v169, v122
	v_cvt_pk_bf16_f32 v118, v162, v163
	v_cvt_pk_bf16_f32 v119, v164, v165
	v_cvt_pk_bf16_f32 v120, v166, v167
	v_cvt_pk_bf16_f32 v121, v168, v169
	ds_read_b128 v[128:131], v170 offset:128
	ds_read_b128 v[184:187], v170 offset:8832
	ds_read_b128 v[188:191], v170 offset:17536
	ds_read_b128 v[192:195], v170 offset:26240
	s_waitcnt lgkmcnt(11)
	v_mfma_f32_32x32x16_bf16 v[154:169], v[98:101], v[10:13], 0
	v_exp_f32_e32 v138, v138
	s_waitcnt lgkmcnt(10)
	v_mfma_f32_32x32x16_bf16 v[154:169], v[102:105], v[14:17], v[154:169]
	v_exp_f32_e32 v139, v139
	v_exp_f32_e32 v140, v140
	s_waitcnt lgkmcnt(9)
	v_mfma_f32_32x32x16_bf16 v[18:33], v[196:199], v[118:121], v[18:33]
	v_exp_f32_e32 v141, v141
	v_exp_f32_e32 v142, v142
	s_waitcnt vmcnt(3)
	ds_write_b128 v171, v[82:85] offset:0
	s_waitcnt vmcnt(2)
	ds_write_b128 v171, v[86:89] offset:8704
	s_waitcnt vmcnt(1)
	ds_write_b128 v171, v[90:93] offset:17408
	s_waitcnt vmcnt(0)
	ds_write_b128 v171, v[94:97] offset:26112
	v_exp_f32_e32 v143, v143
	s_waitcnt lgkmcnt(12)
	v_mfma_f32_32x32x16_bf16 v[34:49], v[216:219], v[118:121], v[34:49]
	v_exp_f32_e32 v144, v144
	v_exp_f32_e32 v145, v145
	v_add_f32_e32 v122, v138, v122
	s_waitcnt lgkmcnt(11)
	v_mfma_f32_32x32x16_bf16 v[50:65], v[200:203], v[118:121], v[50:65]
	v_add_f32_e32 v122, v139, v122
	v_add_f32_e32 v122, v140, v122
	v_add_f32_e32 v122, v141, v122
	s_waitcnt lgkmcnt(10)
	v_mfma_f32_32x32x16_bf16 v[66:81], v[204:207], v[118:121], v[66:81]
	v_add_f32_e32 v122, v142, v122
	v_add_f32_e32 v122, v143, v122
	v_add_f32_e32 v122, v144, v122
	v_add_f32_e32 v122, v145, v122
	v_cvt_pk_bf16_f32 v114, v138, v139
	v_cvt_pk_bf16_f32 v115, v140, v141
	v_cvt_pk_bf16_f32 v116, v142, v143
	v_cvt_pk_bf16_f32 v117, v144, v145
	ds_read_b128 v[196:199], v170 offset:160
	ds_read_b128 v[216:219], v170 offset:8864
	ds_read_b128 v[200:203], v170 offset:17568
	ds_read_b128 v[204:207], v170 offset:26272
	s_waitcnt lgkmcnt(13)
	v_mfma_f32_32x32x16_bf16 v[154:169], v[106:109], v[2:5], v[154:169]
	v_exp_f32_e32 v146, v146
	s_waitcnt lgkmcnt(12)
	v_mfma_f32_32x32x16_bf16 v[154:169], v[110:113], v[6:9], v[154:169]
	v_exp_f32_e32 v147, v147
	v_exp_f32_e32 v148, v148
	s_waitcnt lgkmcnt(11)
	v_mfma_f32_32x32x16_bf16 v[18:33], v[128:131], v[114:117], v[18:33]
	v_exp_f32_e32 v149, v149
	v_exp_f32_e32 v150, v150
	global_load_dwordx4 v[82:85], v125, s[72:73]
	global_load_dwordx4 v[86:89], v125, s[74:75]
	global_load_dwordx4 v[90:93], v125, s[76:77]
	global_load_dwordx4 v[94:97], v125, s[78:79]
	v_add_u32_e32 v125, s38, v125
	v_exp_f32_e32 v151, v151
	s_waitcnt lgkmcnt(10)
	v_mfma_f32_32x32x16_bf16 v[34:49], v[184:187], v[114:117], v[34:49]
	v_exp_f32_e32 v152, v152
	v_exp_f32_e32 v153, v153
	v_add_f32_e32 v122, v146, v122
	s_waitcnt lgkmcnt(9)
	v_mfma_f32_32x32x16_bf16 v[50:65], v[188:191], v[114:117], v[50:65]
	v_add_f32_e32 v122, v147, v122
	v_add_f32_e32 v122, v148, v122
	v_add_f32_e32 v122, v149, v122
	s_waitcnt lgkmcnt(8)
	v_mfma_f32_32x32x16_bf16 v[66:81], v[192:195], v[114:117], v[66:81]
	v_add_f32_e32 v122, v150, v122
	v_add_f32_e32 v122, v151, v122
	v_add_f32_e32 v122, v152, v122
	v_add_f32_e32 v122, v153, v122
	v_cvt_pk_bf16_f32 v118, v146, v147
	v_cvt_pk_bf16_f32 v119, v148, v149
	v_cvt_pk_bf16_f32 v120, v150, v151
	v_cvt_pk_bf16_f32 v121, v152, v153
	ds_read_b128 v[128:131], v170 offset:192
	ds_read_b128 v[184:187], v170 offset:8896
	ds_read_b128 v[188:191], v170 offset:17600
	ds_read_b128 v[192:195], v170 offset:26304
	s_waitcnt lgkmcnt(7)
	v_mfma_f32_32x32x16_bf16 v[18:33], v[196:199], v[118:121], v[18:33]
	v_exp_f32_e32 v154, v154
	v_exp_f32_e32 v155, v155
	v_exp_f32_e32 v156, v156
	s_waitcnt lgkmcnt(6)
	v_mfma_f32_32x32x16_bf16 v[34:49], v[216:219], v[118:121], v[34:49]
	v_exp_f32_e32 v157, v157
	v_exp_f32_e32 v158, v158
	v_exp_f32_e32 v159, v159
	s_waitcnt lgkmcnt(5)
	v_mfma_f32_32x32x16_bf16 v[50:65], v[200:203], v[118:121], v[50:65]
	v_exp_f32_e32 v160, v160
	v_exp_f32_e32 v161, v161
	v_add_f32_e32 v122, v154, v122
	v_add_f32_e32 v122, v155, v122
	s_waitcnt lgkmcnt(4)
	v_mfma_f32_32x32x16_bf16 v[66:81], v[204:207], v[118:121], v[66:81]
	v_add_f32_e32 v122, v156, v122
	v_add_f32_e32 v122, v157, v122
	v_add_f32_e32 v122, v158, v122
	v_add_f32_e32 v122, v159, v122
	v_add_f32_e32 v122, v160, v122
	v_add_f32_e32 v122, v161, v122
	v_cvt_pk_bf16_f32 v114, v154, v155
	v_cvt_pk_bf16_f32 v115, v156, v157
	v_cvt_pk_bf16_f32 v116, v158, v159
	v_cvt_pk_bf16_f32 v117, v160, v161
	ds_read_b128 v[196:199], v170 offset:224
	ds_read_b128 v[216:219], v170 offset:8928
	ds_read_b128 v[200:203], v170 offset:17632
	ds_read_b128 v[204:207], v170 offset:26336
	s_waitcnt lgkmcnt(7)
	v_mfma_f32_32x32x16_bf16 v[18:33], v[128:131], v[114:117], v[18:33]
	v_exp_f32_e32 v162, v162
	v_exp_f32_e32 v163, v163
	v_exp_f32_e32 v164, v164
	s_waitcnt lgkmcnt(6)
	v_mfma_f32_32x32x16_bf16 v[34:49], v[184:187], v[114:117], v[34:49]
	v_exp_f32_e32 v165, v165
	v_exp_f32_e32 v166, v166
	v_exp_f32_e32 v167, v167
	s_waitcnt lgkmcnt(5)
	v_mfma_f32_32x32x16_bf16 v[50:65], v[188:191], v[114:117], v[50:65]
	v_exp_f32_e32 v168, v168
	v_exp_f32_e32 v169, v169
	v_add_f32_e32 v122, v162, v122
	v_add_f32_e32 v122, v163, v122
	s_waitcnt lgkmcnt(4)
	v_mfma_f32_32x32x16_bf16 v[66:81], v[192:195], v[114:117], v[66:81]
	v_add_f32_e32 v122, v164, v122
	v_add_f32_e32 v122, v165, v122
	v_add_f32_e32 v122, v166, v122
	v_add_f32_e32 v122, v167, v122
	v_add_f32_e32 v122, v168, v122
	v_add_f32_e32 v122, v169, v122
	v_cvt_pk_bf16_f32 v118, v162, v163
	v_cvt_pk_bf16_f32 v119, v164, v165
	v_cvt_pk_bf16_f32 v120, v166, v167
	v_cvt_pk_bf16_f32 v121, v168, v169
	s_waitcnt lgkmcnt(3)
	s_nop 0
	v_mfma_f32_32x32x16_bf16 v[18:33], v[196:199], v[118:121], v[18:33]
	s_waitcnt lgkmcnt(2)
	v_mfma_f32_32x32x16_bf16 v[34:49], v[216:219], v[118:121], v[34:49]
	s_waitcnt vmcnt(3)
	ds_write_b128 v173, v[82:85] offset:0
	s_waitcnt vmcnt(2)
	ds_write_b128 v173, v[86:89] offset:8704
	s_waitcnt vmcnt(1)
	ds_write_b128 v173, v[90:93] offset:17408
	s_waitcnt vmcnt(0)
	ds_write_b128 v173, v[94:97] offset:26112
	s_waitcnt lgkmcnt(5)
	v_mfma_f32_32x32x16_bf16 v[50:65], v[200:203], v[118:121], v[50:65]
	s_waitcnt lgkmcnt(4)
	v_mfma_f32_32x32x16_bf16 v[66:81], v[204:207], v[118:121], v[66:81]
	s_waitcnt lgkmcnt(0)
	s_barrier
	s_add_i32 s15, s15, 1
	s_cmp_eq_u32 s15, 34
	s_cbranch_scc0 .Lattn_nf_loop
	v_readlane_b32 s64, v175, 0
	v_readlane_b32 s65, v175, 1
	v_readlane_b32 s66, v175, 2
	v_readlane_b32 s67, v175, 3
	v_readlane_b32 s68, v175, 4
	v_readlane_b32 s69, v175, 5
	v_readlane_b32 s70, v175, 6
	v_readlane_b32 s71, v175, 7
	v_readlane_b32 s72, v175, 8
	v_readlane_b32 s73, v175, 9
	v_readlane_b32 s74, v175, 10
	v_readlane_b32 s75, v175, 11
	v_readlane_b32 s76, v175, 12
	v_readlane_b32 s77, v175, 13
	v_readlane_b32 s78, v175, 14
	v_readlane_b32 s79, v175, 15
	s_nop 4
	v_add_f32_e32 v186, v132, v134
	v_add_f32_e32 v184, v133, v135
	ds_bpermute_b32 v187, v172, v186
	ds_bpermute_b32 v185, v172, v184
	s_mov_b32 s10, 0x3fb8aa3b
	s_mov_b32 s11, 0xc2ce8ed0
	s_mov_b32 s6, 0x42b17218
	v_cmp_eq_u32_e64 s[40:41], 0, v179
	s_lshl_b32 s30, s14, 1
	v_lshlrev_b32_e32 v196, 3, v178
	v_mov_b32_e32 v197, 0
	v_lshlrev_b32_e32 v198, 4, v179
	v_or3_b32 v198, v198, v177, v180
	v_ashrrev_i32_e32 v199, 31, v198
	v_lshlrev_b64 v[198:199], 11, v[198:199]
	s_mov_b64 s[100:101], 0x18a10000
	v_lshl_add_u64 v[198:199], s[42:43], 0, v[198:199]
	v_lshl_add_u64 v[198:199], v[198:199], 0, s[30:31]
	v_lshl_add_u64 v[198:199], v[198:199], 0, v[196:197]
	v_lshl_add_u64 v[198:199], v[198:199], 0, s[100:101]
	global_load_dwordx2 v[146:147], v[198:199], off
	global_load_dwordx2 v[148:149], v[198:199], off offset:32
	global_load_dwordx2 v[150:151], v[198:199], off offset:64
	global_load_dwordx2 v[152:153], v[198:199], off offset:96
	global_load_dwordx2 v[188:189], v[198:199], off offset:128
	global_load_dwordx2 v[190:191], v[198:199], off offset:160
	global_load_dwordx2 v[192:193], v[198:199], off offset:192
	global_load_dwordx2 v[194:195], v[198:199], off offset:224
	s_mov_b64 s[100:101], exec
	s_and_b64 exec, exec, s[4:5]
	s_cbranch_execz .Lpop_skip
	v_readlane_b32 s14, v255, 22
	v_readlane_b32 s15, v255, 23
	v_mov_b32_e32 v224, 1
	s_nop 4
	global_atomic_add v224, v0, v224, s[14:15] sc0
